# prologue conversion-phase streaming stores also marked sc1 (write-through)
# speedup vs baseline: 1.0137x; 1.0049x over previous
; DI unsigned pk2(float a, float b) { f32x2 v = {a, b}; bfx2 r = __builtin_convertvector(v, bfx2); return __builtin_bit_cast(unsigned, r); }
; DI void phase_pro_b(const Params& P) {
;     ...
;     for (size_t i = gtid; i < (size_t)RT * 128; i += gstride) {
;         const int row = (int)(i >> 7), c = (int)(i & 127) * 8;
;         const float* src = row < RL ? P.in[0] + (size_t)row * 1024 + c : P.in[2] + (size_t)(row - RL) * 1024 + c;
;         const int s = row < RL ? (row >> 13) : 4;
;         const float* sh = MOD + (size_t)s * 9216 + c; const float* scl = sh + 1024;
;         unsigned w[4];
; #pragma unroll
;         for (int hf = 0; hf < 2; ++hf) {
;             const f32x4 x = __builtin_nontemporal_load((const f32x4*)(src + 4 * hf)), a = *(const f32x4*)(sh + 4 * hf), g = *(const f32x4*)(scl + 4 * hf);
;             w[2 * hf] = pk2(x[0] * (1.f + g[0]) + a[0], x[1] * (1.f + g[1]) + a[1]);
;             w[2 * hf + 1] = pk2(x[2] * (1.f + g[2]) + a[2], x[3] * (1.f + g[3]) + a[3]);
;         }
;         u32x4 o = {w[0], w[1], w[2], w[3]};
;         *(u32x4*)(XM + (size_t)row * 1024 + c) = o;
;     }
.LBB0_13:
	s_or_b64 exec, exec, s[10:11]
	v_and_b32_e32 v30, 0x3f8, v2
	s_mov_b64 s[10:11], 0x400000
	v_lshlrev_b32_e32 v172, 2, v30
	v_cmp_gt_u64_e32 vcc, s[10:11], v[0:1]
	v_readlane_b32 s10, v253, 7
	v_lshl_add_u64 v[22:23], v[6:7], 0, v[172:173]
	v_cndmask_b32_e32 v6, v196, v0, vcc
	v_readlane_b32 s11, v253, 8
	v_lshrrev_b32_e32 v8, 20, v6
	v_lshlrev_b64 v[4:5], 11, v[4:5]
	v_mov_b64_e32 v[6:7], s[10:11]
	s_mov_b32 s10, 0x9000
	v_mad_u64_u32 v[6:7], s[10:11], v8, s10, v[6:7]
	v_lshl_add_u64 v[26:27], v[6:7], 0, v[172:173]
	s_mov_b64 s[10:11], 0x1000
	v_lshl_add_u64 v[6:7], v[26:27], 0, s[10:11]
	v_add_co_u32_e32 v10, vcc, s28, v26
	global_load_dwordx4 v[6:9], v[6:7], off offset:16
	s_nop 0
	v_addc_co_u32_e32 v11, vcc, 0, v27, vcc
	global_load_dwordx4 v[10:13], v[10:11], off
	s_nop 0
	global_load_dwordx4 v[14:17], v[26:27], off offset:16
	global_load_dwordx4 v[18:21], v[22:23], off offset:16 nt
	s_nop 0
	global_load_dwordx4 v[22:25], v[22:23], off nt
	s_nop 0
	global_load_dwordx4 v[26:29], v[26:27], off
	v_readlane_b32 s10, v253, 5
	v_readlane_b32 s11, v253, 6
	v_lshlrev_b32_e32 v172, 1, v30
	v_lshl_add_u64 v[0:1], v[0:1], 0, s[4:5]
	v_lshl_add_u64 v[4:5], s[10:11], 0, v[4:5]
	s_mov_b64 s[10:11], 0x41ffff
	v_lshl_add_u64 v[30:31], v[4:5], 0, v[172:173]
	v_cmp_lt_u64_e32 vcc, s[10:11], v[0:1]
	s_or_b64 s[8:9], vcc, s[8:9]
	v_lshl_add_u64 v[2:3], v[2:3], 0, s[6:7]
	s_waitcnt vmcnt(5)
	v_pk_add_f32 v[4:5], v[6:7], 1.0 op_sel_hi:[1,0]
	v_pk_add_f32 v[6:7], v[8:9], 1.0 op_sel_hi:[1,0]
	s_waitcnt vmcnt(4)
	v_pk_add_f32 v[8:9], v[10:11], 1.0 op_sel_hi:[1,0]
	v_pk_add_f32 v[10:11], v[12:13], 1.0 op_sel_hi:[1,0]
	s_waitcnt vmcnt(2)
	v_pk_fma_f32 v[4:5], v[18:19], v[4:5], v[14:15]
	v_pk_fma_f32 v[12:13], v[20:21], v[6:7], v[16:17]
	s_waitcnt vmcnt(0)
	v_pk_fma_f32 v[8:9], v[22:23], v[8:9], v[26:27]
	v_pk_fma_f32 v[10:11], v[24:25], v[10:11], v[28:29]
	v_cvt_pk_bf16_f32 v6, v4, v5
	v_cvt_pk_bf16_f32 v7, v12, v13
	v_cvt_pk_bf16_f32 v4, v8, v9
	v_cvt_pk_bf16_f32 v5, v10, v11
	global_store_dwordx4 v[30:31], v[4:7], off sc1
	s_andn2_b64 exec, exec, s[8:9]
	s_cbranch_execz .LBB0_18

; DI unsigned pk2(float a, float b) { f32x2 v = {a, b}; bfx2 r = __builtin_convertvector(v, bfx2); return __builtin_bit_cast(unsigned, r); }
; DI void phase_pro_a(const Params& P, char* smem) {
;     ...
;         for (size_t i0 = gtid; i0 < 1024ull * 704; i0 += 4 * gstride) {
;             f32x4 a[4], b[4];
; #pragma unroll
;             for (int u = 0; u < 4; ++u) {
;                 const size_t i = i0 + u * gstride < 1024ull * 704 ? i0 + u * gstride : i0;
;                 const int k = (int)(i / 704), n = (int)(i % 704) * 8, grp = n >> 6, w = n & 63;
;                 const float* src = ((w < 32) ? sg : su) + (size_t)k * DFF + grp * 32 + (w & 31);
;                 a[u] = __builtin_nontemporal_load((const f32x4*)src); b[u] = __builtin_nontemporal_load((const f32x4*)(src + 4));
;             }
; #pragma unroll
;             for (int u = 0; u < 4; ++u) {
;                 const size_t i = i0 + u * gstride;
;                 if (i < 1024ull * 704) {
;                     const int k = (int)(i / 704), n = (int)(i % 704) * 8;
;                     u32x4 w; w.x = pk2(a[u][0], a[u][1]); w.y = pk2(a[u][2], a[u][3]); w.z = pk2(b[u][0], b[u][1]); w.w = pk2(b[u][2], b[u][3]);
;                     *(u32x4*)(dst + (size_t)k * 5632 + n) = w;
;                 }
;             }
.LBB0_1519:
	v_lshl_add_u64 v[24:25], v[26:27], 0, s[16:17]
	v_cmp_gt_u64_e64 s[6:7], s[76:77], v[24:25]
	s_waitcnt vmcnt(4)
	v_mov_b32_e32 v10, s47
	v_mov_b32_e32 v11, s45
	s_waitcnt vmcnt(1)
	v_cndmask_b32_e64 v4, v26, v24, s[6:7]
	v_cndmask_b32_e64 v2, v27, v25, s[6:7]
	v_mul_hi_u32 v172, v4, s88
	v_mad_u64_u32 v[0:1], s[8:9], v2, s88, v[172:173]
	v_mov_b32_e32 v172, v1
	v_mov_b32_e32 v1, v173
	v_mad_u64_u32 v[0:1], s[8:9], v4, s89, v[0:1]
	v_mov_b32_e32 v0, v1
	v_mov_b32_e32 v1, v173
	v_lshl_add_u64 v[0:1], v[172:173], 0, v[0:1]
	v_mad_u64_u32 v[0:1], s[8:9], v2, s89, v[0:1]
	v_lshrrev_b64 v[2:3], 7, v[0:1]
	v_mul_lo_u32 v0, v2, s90
	v_sub_u32_e32 v6, v4, v0
	v_and_b32_e32 v172, 4, v6
	v_cmp_eq_u64_e64 s[8:9], 0, v[172:173]
	v_mov_b32_e32 v12, s46
	v_mov_b32_e32 v13, s44
	v_cndmask_b32_e64 v5, v10, v11, s[8:9]
	v_cndmask_b32_e64 v4, v12, v13, s[8:9]
	v_lshl_add_u64 v[4:5], v[4:5], 0, s[2:3]
	v_mad_u64_u32 v[2:3], s[8:9], v2, s33, v[4:5]
	v_lshrrev_b32_e32 v0, 7, v1
	v_mad_u32_u24 v3, v0, s33, v3
	v_lshlrev_b32_e32 v0, 4, v6
	v_and_b32_e32 v172, 0x3f80, v0
	v_lshl_add_u64 v[0:1], v[2:3], 0, v[172:173]
	v_lshlrev_b32_e32 v2, 5, v6
	v_and_b32_e32 v172, 0x60, v2
	v_lshl_add_u64 v[2:3], s[20:21], 0, v[26:27]
	v_cmp_gt_u64_e64 s[8:9], s[76:77], v[2:3]
	v_lshl_add_u64 v[0:1], v[0:1], 0, v[172:173]
	v_mov_b32_e32 v49, v173
	v_cndmask_b32_e64 v6, v26, v2, s[8:9]
	v_cndmask_b32_e64 v4, v27, v3, s[8:9]
	v_mul_hi_u32 v172, v6, s88
	v_mad_u64_u32 v[2:3], s[10:11], v4, s88, v[172:173]
	v_mov_b32_e32 v172, v3
	v_mov_b32_e32 v3, v173
	v_mad_u64_u32 v[2:3], s[10:11], v6, s89, v[2:3]
	v_mov_b32_e32 v2, v3
	v_mov_b32_e32 v3, v173
	v_lshl_add_u64 v[2:3], v[172:173], 0, v[2:3]
	v_mad_u64_u32 v[2:3], s[10:11], v4, s89, v[2:3]
	v_lshrrev_b64 v[4:5], 7, v[2:3]
	v_mul_lo_u32 v2, v4, s90
	v_sub_u32_e32 v8, v6, v2
	v_and_b32_e32 v172, 4, v8
	v_cmp_eq_u64_e64 s[10:11], 0, v[172:173]
	v_lshrrev_b32_e32 v2, 7, v3
	s_nop 0
	v_cndmask_b32_e64 v7, v10, v11, s[10:11]
	v_cndmask_b32_e64 v6, v12, v13, s[10:11]
	v_lshl_add_u64 v[6:7], v[6:7], 0, s[2:3]
	v_mad_u64_u32 v[4:5], s[10:11], v4, s33, v[6:7]
	v_mad_u32_u24 v5, v2, s33, v5
	v_lshlrev_b32_e32 v2, 4, v8
	v_and_b32_e32 v172, 0x3f80, v2
	v_lshl_add_u64 v[2:3], v[4:5], 0, v[172:173]
	v_lshlrev_b32_e32 v4, 5, v8
	v_and_b32_e32 v172, 0x60, v4
	v_lshl_add_u64 v[4:5], s[22:23], 0, v[26:27]
	v_cmp_gt_u64_e64 s[10:11], s[76:77], v[4:5]
	v_lshl_add_u64 v[2:3], v[2:3], 0, v[172:173]
	s_nop 0
	v_cndmask_b32_e64 v8, v26, v4, s[10:11]
	v_cndmask_b32_e64 v6, v27, v5, s[10:11]
	v_mul_hi_u32 v172, v8, s88
	v_mad_u64_u32 v[4:5], s[12:13], v6, s88, v[172:173]
	v_mov_b32_e32 v172, v5
	v_mov_b32_e32 v5, v173
	v_mad_u64_u32 v[4:5], s[12:13], v8, s89, v[4:5]
	v_mov_b32_e32 v4, v5
	v_mov_b32_e32 v5, v173
	v_lshl_add_u64 v[4:5], v[172:173], 0, v[4:5]
	v_mad_u64_u32 v[4:5], s[12:13], v6, s89, v[4:5]
	v_lshrrev_b64 v[6:7], 7, v[4:5]
	v_mul_lo_u32 v4, v6, s90
	v_sub_u32_e32 v14, v8, v4
	v_and_b32_e32 v172, 4, v14
	v_cmp_eq_u64_e64 s[12:13], 0, v[172:173]
	v_lshrrev_b32_e32 v4, 7, v5
	s_nop 0
	v_cndmask_b32_e64 v9, v10, v11, s[12:13]
	v_cndmask_b32_e64 v8, v12, v13, s[12:13]
	v_lshl_add_u64 v[8:9], v[8:9], 0, s[2:3]
	v_mad_u64_u32 v[6:7], s[12:13], v6, s33, v[8:9]
	v_mad_u32_u24 v7, v4, s33, v7
	v_lshlrev_b32_e32 v4, 4, v14
	v_and_b32_e32 v172, 0x3f80, v4
	v_lshl_add_u64 v[4:5], v[6:7], 0, v[172:173]
	v_lshlrev_b32_e32 v6, 5, v14
	v_and_b32_e32 v172, 0x60, v6
	v_mul_hi_u32 v6, v26, s88
	v_lshrrev_b32_e32 v8, 9, v6
	v_mul_u32_u24_e32 v6, 0x2c0, v8
	v_sub_u32_e32 v14, v26, v6
	v_and_b32_e32 v6, 4, v14
	v_cmp_eq_u32_e64 s[12:13], 0, v6
	v_lshl_add_u64 v[4:5], v[4:5], 0, v[172:173]
	v_mul_u32_u24_e32 v172, 0x2c00, v8
	v_cndmask_b32_e64 v7, v10, v11, s[12:13]
	v_cndmask_b32_e64 v6, v12, v13, s[12:13]
	v_lshl_add_u64 v[6:7], v[6:7], 0, s[2:3]
	v_lshlrev_b32_e32 v48, 4, v14
	v_lshl_add_u64 v[6:7], v[6:7], 0, v[172:173]
	v_and_b32_e32 v8, 0x3f80, v48
	v_mov_b32_e32 v9, v173
	v_lshl_add_u64 v[6:7], v[6:7], 0, v[8:9]
	v_lshlrev_b32_e32 v8, 5, v14
	v_and_b32_e32 v8, 0x60, v8
	v_lshl_add_u64 v[6:7], v[6:7], 0, v[8:9]
	global_load_dwordx4 v[28:31], v[6:7], off offset:16 nt
	global_load_dwordx4 v[44:47], v[6:7], off nt
	global_load_dwordx4 v[16:19], v[0:1], off offset:16 nt
	global_load_dwordx4 v[20:23], v[0:1], off nt
	global_load_dwordx4 v[8:11], v[2:3], off offset:16 nt
	global_load_dwordx4 v[12:15], v[2:3], off nt
	s_nop 0
	global_load_dwordx4 v[0:3], v[4:5], off offset:16 nt
	s_nop 0
	global_load_dwordx4 v[4:7], v[4:5], off nt
	v_lshl_add_u64 v[50:51], s[30:31], 0, v[172:173]
	s_waitcnt vmcnt(6)
	v_cvt_pk_bf16_f32 v44, v44, v45
	v_cvt_pk_bf16_f32 v45, v46, v47
	v_cvt_pk_bf16_f32 v46, v28, v29
	v_cvt_pk_bf16_f32 v47, v30, v31
	v_lshl_add_u64 v[28:29], v[50:51], 0, v[48:49]
	global_store_dwordx4 v[28:29], v[44:47], off sc1
	s_and_saveexec_b64 s[12:13], s[6:7]
	s_cbranch_execnz .LBB0_1522
	s_or_b64 exec, exec, s[12:13]
	s_and_saveexec_b64 s[6:7], s[8:9]
	s_cbranch_execnz .LBB0_1523

; DI unsigned pk2(float a, float b) { f32x2 v = {a, b}; bfx2 r = __builtin_convertvector(v, bfx2); return __builtin_bit_cast(unsigned, r); }
; DI void phase_pro_a(const Params& P, char* smem) {
;     ...
; #pragma unroll
;             for (int u = 0; u < 4; ++u) {
;                 const size_t i = i0 + u * gstride;
;                 if (i < 1024ull * 704) {
;                     const int k = (int)(i / 704), n = (int)(i % 704) * 8;
;                     u32x4 w; w.x = pk2(a[u][0], a[u][1]); w.y = pk2(a[u][2], a[u][3]); w.z = pk2(b[u][0], b[u][1]); w.w = pk2(b[u][2], b[u][3]);
;                     *(u32x4*)(dst + (size_t)k * 5632 + n) = w;
;                 }
;             }
.LBB0_1522:
	v_add_u32_e32 v27, s37, v26
	v_mul_hi_u32 v28, v27, s88
	v_lshrrev_b32_e32 v28, 9, v28
	v_mul_u32_u24_e32 v29, 0x2c0, v28
	v_sub_u32_e32 v27, v27, v29
	v_mul_u32_u24_e32 v172, 0x2c00, v28
	s_waitcnt vmcnt(5)
	v_cvt_pk_bf16_f32 v20, v20, v21
	v_cvt_pk_bf16_f32 v21, v22, v23
	v_cvt_pk_bf16_f32 v22, v16, v17
	v_lshl_add_u64 v[16:17], s[30:31], 0, v[172:173]
	v_lshlrev_b32_e32 v172, 4, v27
	v_cvt_pk_bf16_f32 v23, v18, v19
	v_lshl_add_u64 v[16:17], v[16:17], 0, v[172:173]
	global_store_dwordx4 v[16:17], v[20:23], off sc1
	s_or_b64 exec, exec, s[12:13]
	s_and_saveexec_b64 s[6:7], s[8:9]
	s_cbranch_execz .LBB0_1521
.LBB0_1523:
	s_waitcnt vmcnt(6)
	v_add_u32_e32 v16, s36, v26
	v_mul_hi_u32 v17, v16, s88
	v_lshrrev_b32_e32 v17, 9, v17
	v_mul_u32_u24_e32 v18, 0x2c0, v17
	v_sub_u32_e32 v16, v16, v18
	v_mul_u32_u24_e32 v172, 0x2c00, v17
	s_waitcnt vmcnt(3)
	v_cvt_pk_bf16_f32 v12, v12, v13
	v_cvt_pk_bf16_f32 v13, v14, v15
	v_cvt_pk_bf16_f32 v14, v8, v9
	v_lshl_add_u64 v[8:9], s[30:31], 0, v[172:173]
	v_lshlrev_b32_e32 v172, 4, v16
	v_cvt_pk_bf16_f32 v15, v10, v11
	v_lshl_add_u64 v[8:9], v[8:9], 0, v[172:173]
	global_store_dwordx4 v[8:9], v[12:15], off sc1
	s_or_b64 exec, exec, s[6:7]
	s_and_saveexec_b64 s[6:7], s[10:11]
	s_cbranch_execz .LBB0_1518
.LBB0_1524:
	s_waitcnt vmcnt(4)
	v_add_u32_e32 v8, s22, v26
	v_mul_hi_u32 v9, v8, s88
	v_lshrrev_b32_e32 v9, 9, v9
	v_mul_u32_u24_e32 v10, 0x2c0, v9
	v_sub_u32_e32 v8, v8, v10
	v_mul_u32_u24_e32 v172, 0x2c00, v9
	s_waitcnt vmcnt(1)
	v_cvt_pk_bf16_f32 v4, v4, v5
	v_cvt_pk_bf16_f32 v5, v6, v7
	v_cvt_pk_bf16_f32 v6, v0, v1
	v_lshl_add_u64 v[0:1], s[30:31], 0, v[172:173]
	v_lshlrev_b32_e32 v172, 4, v8
	v_cvt_pk_bf16_f32 v7, v2, v3
	v_lshl_add_u64 v[0:1], v[0:1], 0, v[172:173]
	global_store_dwordx4 v[0:1], v[4:7], off sc1
	s_branch .LBB0_1518

; DI unsigned pk2(float a, float b) { f32x2 v = {a, b}; bfx2 r = __builtin_convertvector(v, bfx2); return __builtin_bit_cast(unsigned, r); }
; DI void cvt_rows(bf16_t* dst, int ldd, const float* src, int lds_, int rows, int cols_src, const float* rowscale, size_t gtid, size_t gstride) {
;     ...
;             a[u] = __builtin_nontemporal_load((const f32x4*)p); b[u] = __builtin_nontemporal_load((const f32x4*)(p + 4));
;             sc[u] = !ok ? 0.f : (rowscale ? rowscale[k] : 1.f);
;         }
; #pragma unroll
;         for (int u = 0; u < 4; ++u) {
;             const size_t i = i0 + u * gstride;
;             if (i < n) {
;                 const int k = (int)(i / c8), c = (int)(i % c8) * 8;
;                 u32x4 w; w.x = pk2(a[u][0] * sc[u], a[u][1] * sc[u]); w.y = pk2(a[u][2] * sc[u], a[u][3] * sc[u]); w.z = pk2(b[u][0] * sc[u], b[u][1] * sc[u]); w.w = pk2(b[u][2] * sc[u], b[u][3] * sc[u]);
;                 *(u32x4*)(dst + (size_t)k * ldd + c) = w;
.LBB0_1541:
	s_or_b64 exec, exec, s[12:13]
	global_load_dwordx4 v[28:31], v[28:29], off nt
	s_waitcnt vmcnt(3)
	v_cvt_pk_bf16_f32 v4, v4, v5
	v_cvt_pk_bf16_f32 v5, v6, v7
	v_cvt_pk_bf16_f32 v6, v0, v1
	v_cvt_pk_bf16_f32 v7, v2, v3
	v_lshl_add_u64 v[0:1], v[52:53], 1, v[46:47]
	global_store_dwordx4 v[0:1], v[4:7], off sc1
	s_and_saveexec_b64 s[12:13], s[6:7]
	s_cbranch_execnz .LBB0_1544
	s_or_b64 exec, exec, s[12:13]
	s_and_saveexec_b64 s[6:7], s[8:9]
	s_cbranch_execnz .LBB0_1545

; DI unsigned pk2(float a, float b) { f32x2 v = {a, b}; bfx2 r = __builtin_convertvector(v, bfx2); return __builtin_bit_cast(unsigned, r); }
; DI void cvt_rows(bf16_t* dst, int ldd, const float* src, int lds_, int rows, int cols_src, const float* rowscale, size_t gtid, size_t gstride) {
;     ...
; #pragma unroll
;         for (int u = 0; u < 4; ++u) {
;             const size_t i = i0 + u * gstride;
;             if (i < n) {
;                 const int k = (int)(i / c8), c = (int)(i % c8) * 8;
;                 u32x4 w; w.x = pk2(a[u][0] * sc[u], a[u][1] * sc[u]); w.y = pk2(a[u][2] * sc[u], a[u][3] * sc[u]); w.z = pk2(b[u][0] * sc[u], b[u][1] * sc[u]); w.w = pk2(b[u][2] * sc[u], b[u][3] * sc[u]);
;                 *(u32x4*)(dst + (size_t)k * ldd + c) = w;
;             }
.LBB0_1544:
	v_pk_mul_f32 v[0:1], v[54:55], v[8:9] op_sel_hi:[0,1]
	v_pk_mul_f32 v[2:3], v[54:55], v[10:11] op_sel_hi:[0,1]
	v_cvt_pk_bf16_f32 v0, v0, v1
	v_cvt_pk_bf16_f32 v1, v2, v3
	s_waitcnt vmcnt(3)
	v_pk_mul_f32 v[2:3], v[54:55], v[16:17] op_sel_hi:[0,1]
	v_pk_mul_f32 v[4:5], v[54:55], v[18:19] op_sel_hi:[0,1]
	v_cvt_pk_bf16_f32 v2, v2, v3
	v_cvt_pk_bf16_f32 v3, v4, v5
	v_and_b32_e32 v4, 0x3ffc00, v55
	v_lshlrev_b32_e32 v172, 1, v4
	v_lshl_add_u64 v[4:5], v[46:47], 0, v[172:173]
	global_store_dwordx4 v[4:5], v[0:3], off sc1
	s_or_b64 exec, exec, s[12:13]
	s_and_saveexec_b64 s[6:7], s[8:9]
	s_cbranch_execz .LBB0_1543
.LBB0_1545:
	s_waitcnt vmcnt(3)
	v_pk_mul_f32 v[0:1], v[56:57], v[12:13] op_sel_hi:[0,1]
	v_pk_mul_f32 v[2:3], v[56:57], v[14:15] op_sel_hi:[0,1]
	v_cvt_pk_bf16_f32 v0, v0, v1
	v_cvt_pk_bf16_f32 v1, v2, v3
	s_waitcnt vmcnt(2)
	v_pk_mul_f32 v[2:3], v[56:57], v[24:25] op_sel_hi:[0,1]
	v_pk_mul_f32 v[4:5], v[56:57], v[26:27] op_sel_hi:[0,1]
	v_cvt_pk_bf16_f32 v2, v2, v3
	v_cvt_pk_bf16_f32 v3, v4, v5
	v_and_b32_e32 v4, 0x3ffc00, v57
	v_lshlrev_b32_e32 v172, 1, v4
	v_lshl_add_u64 v[4:5], v[46:47], 0, v[172:173]
	global_store_dwordx4 v[4:5], v[0:3], off sc1
	s_or_b64 exec, exec, s[6:7]
	s_and_saveexec_b64 s[6:7], s[10:11]
	s_cbranch_execz .LBB0_1528
.LBB0_1546:
	s_waitcnt vmcnt(2)
	v_pk_mul_f32 v[0:1], v[58:59], v[20:21] op_sel_hi:[0,1]
	v_pk_mul_f32 v[2:3], v[58:59], v[22:23] op_sel_hi:[0,1]
	v_cvt_pk_bf16_f32 v0, v0, v1
	v_cvt_pk_bf16_f32 v1, v2, v3
	s_waitcnt vmcnt(1)
	v_pk_mul_f32 v[2:3], v[58:59], v[28:29] op_sel_hi:[0,1]
	v_pk_mul_f32 v[4:5], v[58:59], v[30:31] op_sel_hi:[0,1]
	v_cvt_pk_bf16_f32 v2, v2, v3
	v_cvt_pk_bf16_f32 v3, v4, v5
	v_and_b32_e32 v4, 0x3ffc00, v59
	v_lshlrev_b32_e32 v172, 1, v4
	v_lshl_add_u64 v[4:5], v[46:47], 0, v[172:173]
	global_store_dwordx4 v[4:5], v[0:3], off sc1
	s_branch .LBB0_1528

; DI unsigned pk2(float a, float b) { f32x2 v = {a, b}; bfx2 r = __builtin_convertvector(v, bfx2); return __builtin_bit_cast(unsigned, r); }
; DI void cvt_rows(bf16_t* dst, int ldd, const float* src, int lds_, int rows, int cols_src, const float* rowscale, size_t gtid, size_t gstride) {
;     ...
;             a[u] = __builtin_nontemporal_load((const f32x4*)p); b[u] = __builtin_nontemporal_load((const f32x4*)(p + 4));
;             sc[u] = !ok ? 0.f : (rowscale ? rowscale[k] : 1.f);
;         }
; #pragma unroll
;         for (int u = 0; u < 4; ++u) {
;             const size_t i = i0 + u * gstride;
;             if (i < n) {
;                 const int k = (int)(i / c8), c = (int)(i % c8) * 8;
;                 u32x4 w; w.x = pk2(a[u][0] * sc[u], a[u][1] * sc[u]); w.y = pk2(a[u][2] * sc[u], a[u][3] * sc[u]); w.z = pk2(b[u][0] * sc[u], b[u][1] * sc[u]); w.w = pk2(b[u][2] * sc[u], b[u][3] * sc[u]);
;                 *(u32x4*)(dst + (size_t)k * ldd + c) = w;
.LBB0_1566:
	s_or_b64 exec, exec, s[30:31]
	global_load_dwordx4 v[28:31], v[28:29], off nt
	s_waitcnt vmcnt(4)
	v_pk_mul_f32 v[0:1], v[54:55], v[0:1] op_sel_hi:[0,1]
	v_pk_mul_f32 v[2:3], v[54:55], v[2:3] op_sel_hi:[0,1]
	v_cvt_pk_bf16_f32 v0, v0, v1
	v_cvt_pk_bf16_f32 v1, v2, v3
	s_waitcnt vmcnt(3)
	v_pk_mul_f32 v[2:3], v[54:55], v[8:9] op_sel_hi:[0,1]
	v_pk_mul_f32 v[8:9], v[54:55], v[10:11] op_sel_hi:[0,1]
	v_cvt_pk_bf16_f32 v2, v2, v3
	v_cvt_pk_bf16_f32 v3, v8, v9
	v_and_b32_e32 v9, 7, v51
	v_and_b32_e32 v8, 0xfffff800, v50
	v_lshl_add_u64 v[8:9], v[8:9], 1, v[48:49]
	global_store_dwordx4 v[8:9], v[0:3], off sc1
	s_and_saveexec_b64 s[30:31], vcc
	s_cbranch_execnz .LBB0_1569
	s_or_b64 exec, exec, s[30:31]
	s_and_saveexec_b64 s[30:31], s[6:7]
	s_cbranch_execnz .LBB0_1570

; DI unsigned pk2(float a, float b) { f32x2 v = {a, b}; bfx2 r = __builtin_convertvector(v, bfx2); return __builtin_bit_cast(unsigned, r); }
; DI void cvt_rows(bf16_t* dst, int ldd, const float* src, int lds_, int rows, int cols_src, const float* rowscale, size_t gtid, size_t gstride) {
;     ...
; #pragma unroll
;         for (int u = 0; u < 4; ++u) {
;             const size_t i = i0 + u * gstride;
;             if (i < n) {
;                 const int k = (int)(i / c8), c = (int)(i % c8) * 8;
;                 u32x4 w; w.x = pk2(a[u][0] * sc[u], a[u][1] * sc[u]); w.y = pk2(a[u][2] * sc[u], a[u][3] * sc[u]); w.z = pk2(b[u][0] * sc[u], b[u][1] * sc[u]); w.w = pk2(b[u][2] * sc[u], b[u][3] * sc[u]);
;                 *(u32x4*)(dst + (size_t)k * ldd + c) = w;
;             }
.LBB0_1569:
	v_pk_mul_f32 v[0:1], v[56:57], v[4:5] op_sel_hi:[0,1]
	v_pk_mul_f32 v[2:3], v[56:57], v[6:7] op_sel_hi:[0,1]
	v_cvt_pk_bf16_f32 v0, v0, v1
	v_cvt_pk_bf16_f32 v1, v2, v3
	s_waitcnt vmcnt(3)
	v_pk_mul_f32 v[2:3], v[56:57], v[16:17] op_sel_hi:[0,1]
	v_pk_mul_f32 v[4:5], v[56:57], v[18:19] op_sel_hi:[0,1]
	v_cvt_pk_bf16_f32 v2, v2, v3
	v_cvt_pk_bf16_f32 v3, v4, v5
	v_add_u32_e32 v4, s28, v50
	v_and_b32_e32 v4, 0x1ff800, v4
	v_lshlrev_b32_e32 v172, 1, v4
	v_lshl_add_u64 v[4:5], v[48:49], 0, v[172:173]
	global_store_dwordx4 v[4:5], v[0:3], off sc1
	s_or_b64 exec, exec, s[30:31]
	s_and_saveexec_b64 s[30:31], s[6:7]
	s_cbranch_execz .LBB0_1568
.LBB0_1570:
	s_waitcnt vmcnt(3)
	v_pk_mul_f32 v[0:1], v[58:59], v[12:13] op_sel_hi:[0,1]
	v_pk_mul_f32 v[2:3], v[58:59], v[14:15] op_sel_hi:[0,1]
	v_cvt_pk_bf16_f32 v0, v0, v1
	v_cvt_pk_bf16_f32 v1, v2, v3
	s_waitcnt vmcnt(2)
	v_pk_mul_f32 v[2:3], v[58:59], v[24:25] op_sel_hi:[0,1]
	v_pk_mul_f32 v[4:5], v[58:59], v[26:27] op_sel_hi:[0,1]
	v_cvt_pk_bf16_f32 v2, v2, v3
	v_cvt_pk_bf16_f32 v3, v4, v5
	v_add_u32_e32 v4, s24, v50
	v_and_b32_e32 v4, 0x1ff800, v4
	v_lshlrev_b32_e32 v172, 1, v4
	v_lshl_add_u64 v[4:5], v[48:49], 0, v[172:173]
	global_store_dwordx4 v[4:5], v[0:3], off sc1
	s_or_b64 exec, exec, s[30:31]
	s_and_saveexec_b64 s[6:7], s[8:9]
	s_cbranch_execz .LBB0_1549
.LBB0_1571:
	s_waitcnt vmcnt(2)
	v_pk_mul_f32 v[0:1], v[60:61], v[20:21] op_sel_hi:[0,1]
	v_pk_mul_f32 v[2:3], v[60:61], v[22:23] op_sel_hi:[0,1]
	v_cvt_pk_bf16_f32 v0, v0, v1
	v_cvt_pk_bf16_f32 v1, v2, v3
	s_waitcnt vmcnt(1)
	v_pk_mul_f32 v[2:3], v[60:61], v[28:29] op_sel_hi:[0,1]
	v_pk_mul_f32 v[4:5], v[60:61], v[30:31] op_sel_hi:[0,1]
	v_cvt_pk_bf16_f32 v2, v2, v3
	v_cvt_pk_bf16_f32 v3, v4, v5
	v_add_u32_e32 v4, s25, v50
	v_and_b32_e32 v4, 0x1ff800, v4
	v_lshlrev_b32_e32 v172, 1, v4
	v_lshl_add_u64 v[4:5], v[48:49], 0, v[172:173]
	global_store_dwordx4 v[4:5], v[0:3], off sc1
	s_branch .LBB0_1549

; DI unsigned pk2(float a, float b) { f32x2 v = {a, b}; bfx2 r = __builtin_convertvector(v, bfx2); return __builtin_bit_cast(unsigned, r); }
; DI void cvt_rows(bf16_t* dst, int ldd, const float* src, int lds_, int rows, int cols_src, const float* rowscale, size_t gtid, size_t gstride) {
;     ...
;             a[u] = __builtin_nontemporal_load((const f32x4*)p); b[u] = __builtin_nontemporal_load((const f32x4*)(p + 4));
;             sc[u] = !ok ? 0.f : (rowscale ? rowscale[k] : 1.f);
;         }
; #pragma unroll
;         for (int u = 0; u < 4; ++u) {
;             const size_t i = i0 + u * gstride;
;             if (i < n) {
;                 const int k = (int)(i / c8), c = (int)(i % c8) * 8;
;                 u32x4 w; w.x = pk2(a[u][0] * sc[u], a[u][1] * sc[u]); w.y = pk2(a[u][2] * sc[u], a[u][3] * sc[u]); w.z = pk2(b[u][0] * sc[u], b[u][1] * sc[u]); w.w = pk2(b[u][2] * sc[u], b[u][3] * sc[u]);
;                 *(u32x4*)(dst + (size_t)k * ldd + c) = w;
.LBB0_1587:
	s_or_b64 exec, exec, s[12:13]
	global_load_dwordx4 v[28:31], v[28:29], off nt
	s_waitcnt vmcnt(3)
	v_cvt_pk_bf16_f32 v4, v4, v5
	v_cvt_pk_bf16_f32 v5, v6, v7
	v_cvt_pk_bf16_f32 v6, v0, v1
	v_cvt_pk_bf16_f32 v7, v2, v3
	v_lshl_add_u64 v[0:1], v[54:55], 1, v[48:49]
	global_store_dwordx4 v[0:1], v[4:7], off sc1
	s_and_saveexec_b64 s[12:13], vcc
	s_cbranch_execnz .LBB0_1590
	s_or_b64 exec, exec, s[12:13]
	s_and_saveexec_b64 s[12:13], s[8:9]
	s_cbranch_execnz .LBB0_1591

; DI unsigned pk2(float a, float b) { f32x2 v = {a, b}; bfx2 r = __builtin_convertvector(v, bfx2); return __builtin_bit_cast(unsigned, r); }
; DI void cvt_rows(bf16_t* dst, int ldd, const float* src, int lds_, int rows, int cols_src, const float* rowscale, size_t gtid, size_t gstride) {
;     ...
; #pragma unroll
;         for (int u = 0; u < 4; ++u) {
;             const size_t i = i0 + u * gstride;
;             if (i < n) {
;                 const int k = (int)(i / c8), c = (int)(i % c8) * 8;
;                 u32x4 w; w.x = pk2(a[u][0] * sc[u], a[u][1] * sc[u]); w.y = pk2(a[u][2] * sc[u], a[u][3] * sc[u]); w.z = pk2(b[u][0] * sc[u], b[u][1] * sc[u]); w.w = pk2(b[u][2] * sc[u], b[u][3] * sc[u]);
;                 *(u32x4*)(dst + (size_t)k * ldd + c) = w;
;             }
.LBB0_1590:
	v_pk_mul_f32 v[0:1], v[56:57], v[8:9] op_sel_hi:[0,1]
	v_pk_mul_f32 v[2:3], v[56:57], v[10:11] op_sel_hi:[0,1]
	v_cvt_pk_bf16_f32 v0, v0, v1
	v_cvt_pk_bf16_f32 v1, v2, v3
	s_waitcnt vmcnt(3)
	v_pk_mul_f32 v[2:3], v[56:57], v[16:17] op_sel_hi:[0,1]
	v_pk_mul_f32 v[4:5], v[56:57], v[18:19] op_sel_hi:[0,1]
	v_cvt_pk_bf16_f32 v2, v2, v3
	v_cvt_pk_bf16_f32 v3, v4, v5
	v_and_b32_e32 v4, 0xffc00, v43
	v_lshlrev_b32_e32 v172, 1, v4
	v_lshl_add_u64 v[4:5], v[48:49], 0, v[172:173]
	global_store_dwordx4 v[4:5], v[0:3], off sc1
	s_or_b64 exec, exec, s[12:13]
	s_and_saveexec_b64 s[12:13], s[8:9]
	s_cbranch_execz .LBB0_1589
.LBB0_1591:
	s_waitcnt vmcnt(3)
	v_pk_mul_f32 v[0:1], v[58:59], v[12:13] op_sel_hi:[0,1]
	v_pk_mul_f32 v[2:3], v[58:59], v[14:15] op_sel_hi:[0,1]
	v_cvt_pk_bf16_f32 v0, v0, v1
	v_cvt_pk_bf16_f32 v1, v2, v3
	s_waitcnt vmcnt(2)
	v_pk_mul_f32 v[2:3], v[58:59], v[24:25] op_sel_hi:[0,1]
	v_pk_mul_f32 v[4:5], v[58:59], v[26:27] op_sel_hi:[0,1]
	v_cvt_pk_bf16_f32 v2, v2, v3
	v_cvt_pk_bf16_f32 v3, v4, v5
	v_and_b32_e32 v4, 0xffc00, v45
	v_lshlrev_b32_e32 v172, 1, v4
	v_lshl_add_u64 v[4:5], v[48:49], 0, v[172:173]
	global_store_dwordx4 v[4:5], v[0:3], off sc1
	s_or_b64 exec, exec, s[12:13]
	s_and_saveexec_b64 s[8:9], s[10:11]
	s_cbranch_execz .LBB0_1574
.LBB0_1592:
	s_waitcnt vmcnt(2)
	v_pk_mul_f32 v[0:1], v[60:61], v[20:21] op_sel_hi:[0,1]
	v_pk_mul_f32 v[2:3], v[60:61], v[22:23] op_sel_hi:[0,1]
	v_cvt_pk_bf16_f32 v0, v0, v1
	v_cvt_pk_bf16_f32 v1, v2, v3
	s_waitcnt vmcnt(1)
	v_pk_mul_f32 v[2:3], v[60:61], v[28:29] op_sel_hi:[0,1]
	v_pk_mul_f32 v[4:5], v[60:61], v[30:31] op_sel_hi:[0,1]
	v_cvt_pk_bf16_f32 v2, v2, v3
	v_cvt_pk_bf16_f32 v3, v4, v5
	v_and_b32_e32 v4, 0xffc00, v57
	v_lshlrev_b32_e32 v172, 1, v4
	v_lshl_add_u64 v[4:5], v[48:49], 0, v[172:173]
	global_store_dwordx4 v[4:5], v[0:3], off sc1
	s_branch .LBB0_1574

; DI unsigned pk2(float a, float b) { f32x2 v = {a, b}; bfx2 r = __builtin_convertvector(v, bfx2); return __builtin_bit_cast(unsigned, r); }
; DI void cvt_rows(bf16_t* dst, int ldd, const float* src, int lds_, int rows, int cols_src, const float* rowscale, size_t gtid, size_t gstride) {
;     ...
;             a[u] = __builtin_nontemporal_load((const f32x4*)p); b[u] = __builtin_nontemporal_load((const f32x4*)(p + 4));
;             sc[u] = !ok ? 0.f : (rowscale ? rowscale[k] : 1.f);
;         }
; #pragma unroll
;         for (int u = 0; u < 4; ++u) {
;             const size_t i = i0 + u * gstride;
;             if (i < n) {
;                 const int k = (int)(i / c8), c = (int)(i % c8) * 8;
;                 u32x4 w; w.x = pk2(a[u][0] * sc[u], a[u][1] * sc[u]); w.y = pk2(a[u][2] * sc[u], a[u][3] * sc[u]); w.z = pk2(b[u][0] * sc[u], b[u][1] * sc[u]); w.w = pk2(b[u][2] * sc[u], b[u][3] * sc[u]);
;                 *(u32x4*)(dst + (size_t)k * ldd + c) = w;
.LBB0_1617:
	s_or_b64 exec, exec, s[40:41]
	s_waitcnt vmcnt(0)
	v_pk_mul_f32 v[4:5], v[62:63], v[4:5] op_sel_hi:[0,1]
	v_pk_mul_f32 v[6:7], v[62:63], v[6:7] op_sel_hi:[0,1]
	v_pk_mul_f32 v[0:1], v[0:1], v[62:63] op_sel_hi:[1,0]
	v_readlane_b32 s10, v253, 21
	v_cvt_pk_bf16_f32 v4, v4, v5
	v_cvt_pk_bf16_f32 v5, v6, v7
	v_cvt_pk_bf16_f32 v6, v0, v1
	v_pk_mul_f32 v[0:1], v[2:3], v[62:63] op_sel_hi:[1,0]
	v_readlane_b32 s11, v253, 22
	v_cvt_pk_bf16_f32 v7, v0, v1
	v_lshlrev_b16_e32 v172, 4, v43
	v_mov_b64_e32 v[0:1], s[10:11]
	s_movk_i32 s10, 0x600
	v_mad_u64_u32 v[0:1], s[10:11], v35, s10, v[0:1]
	v_lshl_add_u64 v[0:1], v[0:1], 0, v[172:173]
	global_store_dwordx4 v[0:1], v[4:7], off sc1
	s_and_saveexec_b64 s[10:11], s[8:9]
	s_cbranch_execnz .LBB0_1620
	s_or_b64 exec, exec, s[10:11]
	s_and_saveexec_b64 s[8:9], s[12:13]
	s_cbranch_execnz .LBB0_1621

; DI unsigned pk2(float a, float b) { f32x2 v = {a, b}; bfx2 r = __builtin_convertvector(v, bfx2); return __builtin_bit_cast(unsigned, r); }
; DI void cvt_rows(bf16_t* dst, int ldd, const float* src, int lds_, int rows, int cols_src, const float* rowscale, size_t gtid, size_t gstride) {
;     ...
; #pragma unroll
;         for (int u = 0; u < 4; ++u) {
;             const size_t i = i0 + u * gstride;
;             if (i < n) {
;                 const int k = (int)(i / c8), c = (int)(i % c8) * 8;
;                 u32x4 w; w.x = pk2(a[u][0] * sc[u], a[u][1] * sc[u]); w.y = pk2(a[u][2] * sc[u], a[u][3] * sc[u]); w.z = pk2(b[u][0] * sc[u], b[u][1] * sc[u]); w.w = pk2(b[u][2] * sc[u], b[u][3] * sc[u]);
;                 *(u32x4*)(dst + (size_t)k * ldd + c) = w;
;             }
.LBB0_1620:
	s_movk_i32 s40, 0xfa00
	v_mad_u64_u32 v[4:5], s[8:9], v64, s40, v[54:55]
	v_mov_b32_e32 v0, v5
	v_mad_u64_u32 v[0:1], s[8:9], v65, s40, v[0:1]
	v_sub_u32_e32 v5, v0, v64
	v_pk_mul_f32 v[0:1], v[66:67], v[12:13] op_sel_hi:[0,1]
	v_pk_mul_f32 v[2:3], v[66:67], v[14:15] op_sel_hi:[0,1]
	v_lshrrev_b32_e32 v35, 22, v45
	v_cvt_pk_bf16_f32 v0, v0, v1
	v_cvt_pk_bf16_f32 v1, v2, v3
	v_pk_mul_f32 v[2:3], v[8:9], v[66:67] op_sel_hi:[1,0]
	v_pk_mul_f32 v[6:7], v[10:11], v[66:67] op_sel_hi:[1,0]
	s_movk_i32 s8, 0x600
	v_cvt_pk_bf16_f32 v2, v2, v3
	v_cvt_pk_bf16_f32 v3, v6, v7
	v_mad_u64_u32 v[4:5], s[8:9], v35, s8, v[4:5]
	global_store_dwordx4 v[4:5], v[0:3], off sc1
	s_or_b64 exec, exec, s[10:11]
	s_and_saveexec_b64 s[8:9], s[12:13]
	s_cbranch_execz .LBB0_1619
.LBB0_1621:
	s_movk_i32 s12, 0xfa00
	v_mad_u64_u32 v[4:5], s[10:11], v68, s12, v[50:51]
	v_mov_b32_e32 v0, v5
	v_mad_u64_u32 v[0:1], s[10:11], v69, s12, v[0:1]
	v_sub_u32_e32 v5, v0, v68
	v_pk_mul_f32 v[0:1], v[70:71], v[20:21] op_sel_hi:[0,1]
	v_pk_mul_f32 v[2:3], v[70:71], v[22:23] op_sel_hi:[0,1]
	v_lshrrev_b32_e32 v8, 22, v63
	v_cvt_pk_bf16_f32 v0, v0, v1
	v_cvt_pk_bf16_f32 v1, v2, v3
	v_pk_mul_f32 v[2:3], v[16:17], v[70:71] op_sel_hi:[1,0]
	v_pk_mul_f32 v[6:7], v[18:19], v[70:71] op_sel_hi:[1,0]
	s_movk_i32 s10, 0x600
	v_cvt_pk_bf16_f32 v2, v2, v3
	v_cvt_pk_bf16_f32 v3, v6, v7
	v_mad_u64_u32 v[4:5], s[10:11], v8, s10, v[4:5]
	global_store_dwordx4 v[4:5], v[0:3], off sc1
	s_or_b64 exec, exec, s[8:9]
	s_and_saveexec_b64 s[8:9], s[14:15]
	s_cbranch_execz .LBB0_1595
.LBB0_1622:
	s_movk_i32 s12, 0xfa00
	v_mad_u64_u32 v[4:5], s[10:11], v72, s12, v[58:59]
	v_mov_b32_e32 v0, v5
	v_mad_u64_u32 v[0:1], s[10:11], v73, s12, v[0:1]
	v_sub_u32_e32 v5, v0, v72
	v_pk_mul_f32 v[0:1], v[74:75], v[28:29] op_sel_hi:[0,1]
	v_pk_mul_f32 v[2:3], v[74:75], v[30:31] op_sel_hi:[0,1]
	v_lshrrev_b32_e32 v8, 22, v67
	v_cvt_pk_bf16_f32 v0, v0, v1
	v_cvt_pk_bf16_f32 v1, v2, v3
	v_pk_mul_f32 v[2:3], v[24:25], v[74:75] op_sel_hi:[1,0]
	v_pk_mul_f32 v[6:7], v[26:27], v[74:75] op_sel_hi:[1,0]
	s_movk_i32 s10, 0x600
	v_cvt_pk_bf16_f32 v2, v2, v3
	v_cvt_pk_bf16_f32 v3, v6, v7
	v_mad_u64_u32 v[4:5], s[10:11], v8, s10, v[4:5]
	global_store_dwordx4 v[4:5], v[0:3], off sc1
	s_branch .LBB0_1595

; DI unsigned pk2(float a, float b) { f32x2 v = {a, b}; bfx2 r = __builtin_convertvector(v, bfx2); return __builtin_bit_cast(unsigned, r); }
; DI void cvt_rows(bf16_t* dst, int ldd, const float* src, int lds_, int rows, int cols_src, const float* rowscale, size_t gtid, size_t gstride) {
;     ...
;             a[u] = __builtin_nontemporal_load((const f32x4*)p); b[u] = __builtin_nontemporal_load((const f32x4*)(p + 4));
;             sc[u] = !ok ? 0.f : (rowscale ? rowscale[k] : 1.f);
;         }
; #pragma unroll
;         for (int u = 0; u < 4; ++u) {
;             const size_t i = i0 + u * gstride;
;             if (i < n) {
;                 const int k = (int)(i / c8), c = (int)(i % c8) * 8;
;                 u32x4 w; w.x = pk2(a[u][0] * sc[u], a[u][1] * sc[u]); w.y = pk2(a[u][2] * sc[u], a[u][3] * sc[u]); w.z = pk2(b[u][0] * sc[u], b[u][1] * sc[u]); w.w = pk2(b[u][2] * sc[u], b[u][3] * sc[u]);
;                 *(u32x4*)(dst + (size_t)k * ldd + c) = w;
.LBB0_1647:
	s_or_b64 exec, exec, s[30:31]
	s_waitcnt vmcnt(0)
	v_pk_mul_f32 v[4:5], v[54:55], v[4:5] op_sel_hi:[0,1]
	v_pk_mul_f32 v[6:7], v[54:55], v[6:7] op_sel_hi:[0,1]
	v_pk_mul_f32 v[0:1], v[0:1], v[54:55] op_sel_hi:[1,0]
	v_cvt_pk_bf16_f32 v4, v4, v5
	v_cvt_pk_bf16_f32 v5, v6, v7
	v_cvt_pk_bf16_f32 v6, v0, v1
	v_pk_mul_f32 v[0:1], v[2:3], v[54:55] op_sel_hi:[1,0]
	s_nop 0
	v_cvt_pk_bf16_f32 v7, v0, v1
	v_and_b32_e32 v0, 0x7fc00, v50
	v_lshlrev_b32_e32 v172, 1, v0
	v_lshl_add_u64 v[0:1], v[48:49], 0, v[172:173]
	global_store_dwordx4 v[0:1], v[4:7], off sc1
	s_and_saveexec_b64 s[10:11], s[8:9]
	s_cbranch_execnz .LBB0_1650
	s_or_b64 exec, exec, s[10:11]
	s_and_saveexec_b64 s[8:9], s[12:13]
	s_cbranch_execnz .LBB0_1651

; DI unsigned pk2(float a, float b) { f32x2 v = {a, b}; bfx2 r = __builtin_convertvector(v, bfx2); return __builtin_bit_cast(unsigned, r); }
; DI void cvt_rows(bf16_t* dst, int ldd, const float* src, int lds_, int rows, int cols_src, const float* rowscale, size_t gtid, size_t gstride) {
;     ...
; #pragma unroll
;         for (int u = 0; u < 4; ++u) {
;             const size_t i = i0 + u * gstride;
;             if (i < n) {
;                 const int k = (int)(i / c8), c = (int)(i % c8) * 8;
;                 u32x4 w; w.x = pk2(a[u][0] * sc[u], a[u][1] * sc[u]); w.y = pk2(a[u][2] * sc[u], a[u][3] * sc[u]); w.z = pk2(b[u][0] * sc[u], b[u][1] * sc[u]); w.w = pk2(b[u][2] * sc[u], b[u][3] * sc[u]);
;                 *(u32x4*)(dst + (size_t)k * ldd + c) = w;
;             }
.LBB0_1650:
	v_pk_mul_f32 v[0:1], v[56:57], v[12:13] op_sel_hi:[0,1]
	v_pk_mul_f32 v[2:3], v[56:57], v[14:15] op_sel_hi:[0,1]
	v_cvt_pk_bf16_f32 v0, v0, v1
	v_cvt_pk_bf16_f32 v1, v2, v3
	v_pk_mul_f32 v[2:3], v[8:9], v[56:57] op_sel_hi:[1,0]
	v_pk_mul_f32 v[4:5], v[10:11], v[56:57] op_sel_hi:[1,0]
	v_cvt_pk_bf16_f32 v2, v2, v3
	v_cvt_pk_bf16_f32 v3, v4, v5
	v_add_u32_e32 v4, s28, v50
	v_and_b32_e32 v4, 0x1fc00, v4
	v_lshlrev_b32_e32 v172, 1, v4
	v_lshl_add_u64 v[4:5], v[48:49], 0, v[172:173]
	global_store_dwordx4 v[4:5], v[0:3], off sc1
	s_or_b64 exec, exec, s[10:11]
	s_and_saveexec_b64 s[8:9], s[12:13]
	s_cbranch_execz .LBB0_1649
.LBB0_1651:
	v_pk_mul_f32 v[0:1], v[58:59], v[20:21] op_sel_hi:[0,1]
	v_pk_mul_f32 v[2:3], v[58:59], v[22:23] op_sel_hi:[0,1]
	v_cvt_pk_bf16_f32 v0, v0, v1
	v_cvt_pk_bf16_f32 v1, v2, v3
	v_pk_mul_f32 v[2:3], v[16:17], v[58:59] op_sel_hi:[1,0]
	v_pk_mul_f32 v[4:5], v[18:19], v[58:59] op_sel_hi:[1,0]
	v_cvt_pk_bf16_f32 v2, v2, v3
	v_cvt_pk_bf16_f32 v3, v4, v5
	v_add_u32_e32 v4, s24, v50
	v_and_b32_e32 v4, 0x1fc00, v4
	v_lshlrev_b32_e32 v172, 1, v4
	v_lshl_add_u64 v[4:5], v[48:49], 0, v[172:173]
	global_store_dwordx4 v[4:5], v[0:3], off sc1
	s_or_b64 exec, exec, s[8:9]
	s_and_saveexec_b64 s[8:9], s[14:15]
	s_cbranch_execz .LBB0_1625
.LBB0_1652:
	v_pk_mul_f32 v[0:1], v[60:61], v[28:29] op_sel_hi:[0,1]
	v_pk_mul_f32 v[2:3], v[60:61], v[30:31] op_sel_hi:[0,1]
	v_cvt_pk_bf16_f32 v0, v0, v1
	v_cvt_pk_bf16_f32 v1, v2, v3
	v_pk_mul_f32 v[2:3], v[24:25], v[60:61] op_sel_hi:[1,0]
	v_pk_mul_f32 v[4:5], v[26:27], v[60:61] op_sel_hi:[1,0]
	v_cvt_pk_bf16_f32 v2, v2, v3
	v_cvt_pk_bf16_f32 v3, v4, v5
	v_add_u32_e32 v4, s25, v50
	v_and_b32_e32 v4, 0x1fc00, v4
	v_lshlrev_b32_e32 v172, 1, v4
	v_lshl_add_u64 v[4:5], v[48:49], 0, v[172:173]
	global_store_dwordx4 v[4:5], v[0:3], off sc1
	s_branch .LBB0_1625

; DI unsigned pk2(float a, float b) { f32x2 v = {a, b}; bfx2 r = __builtin_convertvector(v, bfx2); return __builtin_bit_cast(unsigned, r); }
; DI void cvt_rows(bf16_t* dst, int ldd, const float* src, int lds_, int rows, int cols_src, const float* rowscale, size_t gtid, size_t gstride) {
;     ...
;             a[u] = __builtin_nontemporal_load((const f32x4*)p); b[u] = __builtin_nontemporal_load((const f32x4*)(p + 4));
;             sc[u] = !ok ? 0.f : (rowscale ? rowscale[k] : 1.f);
;         }
; #pragma unroll
;         for (int u = 0; u < 4; ++u) {
;             const size_t i = i0 + u * gstride;
;             if (i < n) {
;                 const int k = (int)(i / c8), c = (int)(i % c8) * 8;
;                 u32x4 w; w.x = pk2(a[u][0] * sc[u], a[u][1] * sc[u]); w.y = pk2(a[u][2] * sc[u], a[u][3] * sc[u]); w.z = pk2(b[u][0] * sc[u], b[u][1] * sc[u]); w.w = pk2(b[u][2] * sc[u], b[u][3] * sc[u]);
;                 *(u32x4*)(dst + (size_t)k * ldd + c) = w;
.LBB0_1668:
	s_or_b64 exec, exec, s[10:11]
	global_load_dwordx4 v[28:31], v[28:29], off nt
	s_waitcnt vmcnt(3)
	v_cvt_pk_bf16_f32 v4, v4, v5
	v_cvt_pk_bf16_f32 v5, v6, v7
	v_cvt_pk_bf16_f32 v6, v0, v1
	v_cvt_pk_bf16_f32 v7, v2, v3
	v_lshl_add_u64 v[0:1], v[50:51], 1, v[42:43]
	global_store_dwordx4 v[0:1], v[4:7], off sc1
	s_and_saveexec_b64 s[10:11], vcc
	s_cbranch_execnz .LBB0_1671
	s_or_b64 exec, exec, s[10:11]
	s_and_saveexec_b64 s[10:11], s[4:5]
	s_cbranch_execnz .LBB0_1672

; DI unsigned pk2(float a, float b) { f32x2 v = {a, b}; bfx2 r = __builtin_convertvector(v, bfx2); return __builtin_bit_cast(unsigned, r); }
; DI void cvt_rows(bf16_t* dst, int ldd, const float* src, int lds_, int rows, int cols_src, const float* rowscale, size_t gtid, size_t gstride) {
;     ...
; #pragma unroll
;         for (int u = 0; u < 4; ++u) {
;             const size_t i = i0 + u * gstride;
;             if (i < n) {
;                 const int k = (int)(i / c8), c = (int)(i % c8) * 8;
;                 u32x4 w; w.x = pk2(a[u][0] * sc[u], a[u][1] * sc[u]); w.y = pk2(a[u][2] * sc[u], a[u][3] * sc[u]); w.z = pk2(b[u][0] * sc[u], b[u][1] * sc[u]); w.w = pk2(b[u][2] * sc[u], b[u][3] * sc[u]);
;                 *(u32x4*)(dst + (size_t)k * ldd + c) = w;
;             }
.LBB0_1671:
	v_pk_mul_f32 v[0:1], v[52:53], v[8:9] op_sel_hi:[0,1]
	v_pk_mul_f32 v[2:3], v[52:53], v[10:11] op_sel_hi:[0,1]
	v_cvt_pk_bf16_f32 v0, v0, v1
	v_cvt_pk_bf16_f32 v1, v2, v3
	s_waitcnt vmcnt(3)
	v_pk_mul_f32 v[2:3], v[52:53], v[12:13] op_sel_hi:[0,1]
	v_pk_mul_f32 v[4:5], v[52:53], v[14:15] op_sel_hi:[0,1]
	v_cvt_pk_bf16_f32 v2, v2, v3
	v_cvt_pk_bf16_f32 v3, v4, v5
	v_and_b32_e32 v4, 0x1ff800, v35
	v_lshlrev_b32_e32 v172, 1, v4
	v_lshl_add_u64 v[4:5], v[42:43], 0, v[172:173]
	global_store_dwordx4 v[4:5], v[0:3], off sc1
	s_or_b64 exec, exec, s[10:11]
	s_and_saveexec_b64 s[10:11], s[4:5]
	s_cbranch_execz .LBB0_1670
.LBB0_1672:
	s_waitcnt vmcnt(3)
	v_pk_mul_f32 v[0:1], v[54:55], v[16:17] op_sel_hi:[0,1]
	v_pk_mul_f32 v[2:3], v[54:55], v[18:19] op_sel_hi:[0,1]
	v_cvt_pk_bf16_f32 v0, v0, v1
	v_cvt_pk_bf16_f32 v1, v2, v3
	s_waitcnt vmcnt(2)
	v_pk_mul_f32 v[2:3], v[54:55], v[20:21] op_sel_hi:[0,1]
	v_pk_mul_f32 v[4:5], v[54:55], v[22:23] op_sel_hi:[0,1]
	v_cvt_pk_bf16_f32 v2, v2, v3
	v_cvt_pk_bf16_f32 v3, v4, v5
	v_and_b32_e32 v4, 0x1ff800, v53
	v_lshlrev_b32_e32 v172, 1, v4
	v_lshl_add_u64 v[4:5], v[42:43], 0, v[172:173]
	global_store_dwordx4 v[4:5], v[0:3], off sc1
	s_or_b64 exec, exec, s[10:11]
	s_and_saveexec_b64 s[4:5], s[8:9]
	s_cbranch_execz .LBB0_1655
.LBB0_1673:
	s_waitcnt vmcnt(2)
	v_pk_mul_f32 v[0:1], v[56:57], v[24:25] op_sel_hi:[0,1]
	v_pk_mul_f32 v[2:3], v[56:57], v[26:27] op_sel_hi:[0,1]
	v_cvt_pk_bf16_f32 v0, v0, v1
	v_cvt_pk_bf16_f32 v1, v2, v3
	s_waitcnt vmcnt(1)
	v_pk_mul_f32 v[2:3], v[56:57], v[28:29] op_sel_hi:[0,1]
	v_pk_mul_f32 v[4:5], v[56:57], v[30:31] op_sel_hi:[0,1]
	v_cvt_pk_bf16_f32 v2, v2, v3
	v_cvt_pk_bf16_f32 v3, v4, v5
	v_and_b32_e32 v4, 0x1ff800, v55
	v_lshlrev_b32_e32 v172, 1, v4
	v_lshl_add_u64 v[4:5], v[42:43], 0, v[172:173]
	global_store_dwordx4 v[4:5], v[0:3], off sc1
	s_branch .LBB0_1655

; DI unsigned pk2(float a, float b) { f32x2 v = {a, b}; bfx2 r = __builtin_convertvector(v, bfx2); return __builtin_bit_cast(unsigned, r); }
; DI void cvt_rows(bf16_t* dst, int ldd, const float* src, int lds_, int rows, int cols_src, const float* rowscale, size_t gtid, size_t gstride) {
;     ...
;             a[u] = __builtin_nontemporal_load((const f32x4*)p); b[u] = __builtin_nontemporal_load((const f32x4*)(p + 4));
;             sc[u] = !ok ? 0.f : (rowscale ? rowscale[k] : 1.f);
;         }
; #pragma unroll
;         for (int u = 0; u < 4; ++u) {
;             const size_t i = i0 + u * gstride;
;             if (i < n) {
;                 const int k = (int)(i / c8), c = (int)(i % c8) * 8;
;                 u32x4 w; w.x = pk2(a[u][0] * sc[u], a[u][1] * sc[u]); w.y = pk2(a[u][2] * sc[u], a[u][3] * sc[u]); w.z = pk2(b[u][0] * sc[u], b[u][1] * sc[u]); w.w = pk2(b[u][2] * sc[u], b[u][3] * sc[u]);
;                 *(u32x4*)(dst + (size_t)k * ldd + c) = w;
.LBB0_1689:
	s_or_b64 exec, exec, s[8:9]
	global_load_dwordx4 v[28:31], v[28:29], off nt
	s_waitcnt vmcnt(3)
	v_cvt_pk_bf16_f32 v4, v4, v5
	v_cvt_pk_bf16_f32 v5, v6, v7
	v_cvt_pk_bf16_f32 v6, v0, v1
	v_cvt_pk_bf16_f32 v7, v2, v3
	v_lshl_add_u64 v[0:1], v[44:45], 1, v[38:39]
	global_store_dwordx4 v[0:1], v[4:7], off sc1
	s_and_saveexec_b64 s[8:9], vcc
	s_cbranch_execnz .LBB0_1692
	s_or_b64 exec, exec, s[8:9]
	s_and_saveexec_b64 s[8:9], s[4:5]
	s_cbranch_execnz .LBB0_1693

; DI unsigned pk2(float a, float b) { f32x2 v = {a, b}; bfx2 r = __builtin_convertvector(v, bfx2); return __builtin_bit_cast(unsigned, r); }
; DI void cvt_rows(bf16_t* dst, int ldd, const float* src, int lds_, int rows, int cols_src, const float* rowscale, size_t gtid, size_t gstride) {
;     ...
; #pragma unroll
;         for (int u = 0; u < 4; ++u) {
;             const size_t i = i0 + u * gstride;
;             if (i < n) {
;                 const int k = (int)(i / c8), c = (int)(i % c8) * 8;
;                 u32x4 w; w.x = pk2(a[u][0] * sc[u], a[u][1] * sc[u]); w.y = pk2(a[u][2] * sc[u], a[u][3] * sc[u]); w.z = pk2(b[u][0] * sc[u], b[u][1] * sc[u]); w.w = pk2(b[u][2] * sc[u], b[u][3] * sc[u]);
;                 *(u32x4*)(dst + (size_t)k * ldd + c) = w;
;             }
.LBB0_1692:
	v_pk_mul_f32 v[0:1], v[46:47], v[8:9] op_sel_hi:[0,1]
	v_pk_mul_f32 v[2:3], v[46:47], v[10:11] op_sel_hi:[0,1]
	v_cvt_pk_bf16_f32 v0, v0, v1
	v_cvt_pk_bf16_f32 v1, v2, v3
	s_waitcnt vmcnt(3)
	v_pk_mul_f32 v[2:3], v[46:47], v[12:13] op_sel_hi:[0,1]
	v_pk_mul_f32 v[4:5], v[46:47], v[14:15] op_sel_hi:[0,1]
	v_cvt_pk_bf16_f32 v2, v2, v3
	v_cvt_pk_bf16_f32 v3, v4, v5
	v_and_b32_e32 v4, 0xffc00, v35
	v_lshlrev_b32_e32 v172, 1, v4
	v_lshl_add_u64 v[4:5], v[38:39], 0, v[172:173]
	global_store_dwordx4 v[4:5], v[0:3], off sc1
	s_or_b64 exec, exec, s[8:9]
	s_and_saveexec_b64 s[8:9], s[4:5]
	s_cbranch_execz .LBB0_1691
.LBB0_1693:
	s_waitcnt vmcnt(3)
	v_pk_mul_f32 v[0:1], v[48:49], v[16:17] op_sel_hi:[0,1]
	v_pk_mul_f32 v[2:3], v[48:49], v[18:19] op_sel_hi:[0,1]
	v_cvt_pk_bf16_f32 v0, v0, v1
	v_cvt_pk_bf16_f32 v1, v2, v3
	s_waitcnt vmcnt(2)
	v_pk_mul_f32 v[2:3], v[48:49], v[20:21] op_sel_hi:[0,1]
	v_pk_mul_f32 v[4:5], v[48:49], v[22:23] op_sel_hi:[0,1]
	v_cvt_pk_bf16_f32 v2, v2, v3
	v_cvt_pk_bf16_f32 v3, v4, v5
	v_and_b32_e32 v4, 0xffc00, v47
	v_lshlrev_b32_e32 v172, 1, v4
	v_lshl_add_u64 v[4:5], v[38:39], 0, v[172:173]
	global_store_dwordx4 v[4:5], v[0:3], off sc1
	s_or_b64 exec, exec, s[8:9]
	s_and_saveexec_b64 s[4:5], s[6:7]
	s_cbranch_execz .LBB0_1676
.LBB0_1694:
	s_waitcnt vmcnt(2)
	v_pk_mul_f32 v[0:1], v[50:51], v[24:25] op_sel_hi:[0,1]
	v_pk_mul_f32 v[2:3], v[50:51], v[26:27] op_sel_hi:[0,1]
	v_cvt_pk_bf16_f32 v0, v0, v1
	v_cvt_pk_bf16_f32 v1, v2, v3
	s_waitcnt vmcnt(1)
	v_pk_mul_f32 v[2:3], v[50:51], v[28:29] op_sel_hi:[0,1]
	v_pk_mul_f32 v[4:5], v[50:51], v[30:31] op_sel_hi:[0,1]
	v_cvt_pk_bf16_f32 v2, v2, v3
	v_cvt_pk_bf16_f32 v3, v4, v5
	v_and_b32_e32 v4, 0xffc00, v49
	v_lshlrev_b32_e32 v172, 1, v4
	v_lshl_add_u64 v[4:5], v[38:39], 0, v[172:173]
	global_store_dwordx4 v[4:5], v[0:3], off sc1
	s_branch .LBB0_1676

; DI void phase_pro_a(const Params& P, char* smem) {
;     ...
;     for (size_t i = gtid; i < 512ull * 64; i += gstride) {
;         const int k = (int)(i >> 6), n = (int)(i & 63) * 8;
;         bf16_t* d = (bf16_t*)(ws + OFF_POOL) + (size_t)k * 512 + n;
;         if ((k >> 7) == (n >> 7)) cvt8(d, P.in[21] + (size_t)k * 128 + (n & 127), 1.f);
;         else { u32x4 z = {0u, 0u, 0u, 0u}; *(u32x4*)d = z; }
;     }
.LBB0_1697:
	s_or_b64 exec, exec, s[4:5]
	v_readlane_b32 s4, v253, 53
	v_lshlrev_b64 v[6:7], 10, v[6:7]
	v_readlane_b32 s5, v253, 54
	v_and_b32_e32 v9, 0x1f8, v8
	v_lshl_add_u64 v[4:5], v[4:5], 0, s[16:17]
	v_lshl_add_u64 v[6:7], s[4:5], 0, v[6:7]
	s_mov_b64 s[4:5], 0x7fff
	v_lshlrev_b32_e32 v172, 1, v9
	v_cmp_lt_u64_e32 vcc, s[4:5], v[4:5]
	v_lshl_add_u64 v[6:7], v[6:7], 0, v[172:173]
	s_or_b64 s[2:3], vcc, s[2:3]
	v_add_u32_e32 v8, s6, v8
	global_store_dwordx4 v[6:7], v[0:3], off sc1
	s_andn2_b64 exec, exec, s[2:3]
	s_cbranch_execz .LBB0_1700
